# scan: teams decoupled - per-team LDS counter barrier instead of workgroup s_barrier in the scan loop
# speedup vs baseline: 1.0125x; 1.0125x over previous
.LBB0_327:
	s_andn2_b64 vcc, exec, s[0:1]
	s_cbranch_vccnz .LBB0_856
	v_readlane_b32 s0, v255, 5
	s_cmp_lt_i32 s0, 2
	s_mov_b64 s[0:1], -1
	s_cbranch_scc1 .LBB0_779
	v_readlane_b32 s0, v255, 5
	s_cmp_lt_i32 s0, 3
	s_mov_b64 s[0:1], -1
	s_cbranch_scc1 .LBB0_692
	v_readlane_b32 s0, v255, 5
	s_cmp_gt_i32 s0, 3
	s_mov_b64 s[0:1], -1
	s_cbranch_scc0 .LBB0_389
	s_waitcnt vmcnt(0) lgkmcnt(0)
	v_readlane_b32 s0, v250, 1
	v_readlane_b32 s1, v250, 2
	v_readlane_b32 s3, v250, 0
	v_readlane_b32 s45, v250, 21
	v_readlane_b32 s44, v255, 8
	s_sub_u32 s0, s0, 0xe8
	s_subb_u32 s1, s1, 0
	s_load_dwordx2 s[28:29], s[0:1], 0xd8
	s_load_dwordx2 s[34:35], s[0:1], 0xd0
	s_load_dwordx2 s[36:37], s[0:1], 0x18
	s_load_dwordx2 s[38:39], s[0:1], 0x88
	s_load_dwordx2 s[40:41], s[0:1], 0x90
	s_and_b32 s42, s3, 7
	s_lshr_b32 s43, s3, 3
	s_lshr_b32 s45, s45, 4
	s_and_b32 s46, s43, 15
	s_cmp_gt_u32 s44, 8
	s_cselect_b32 s44, 1, 0
	s_and_b32 s47, s45, 3
	s_mov_b32 s59, 0x40da000
	s_mov_b32 s49, 0
	s_mov_b32 s50, 0x3000000
	s_cmp_eq_u32 s47, 1
	s_cselect_b32 s59, 0x70da000, s59
	s_cmp_eq_u32 s47, 2
	s_cselect_b32 s59, 0x1fcda000, s59
	s_cselect_b32 s49, s50, s49
	s_cmp_eq_u32 s47, 3
	s_cselect_b32 s59, 0x25cda000, s59
	s_cselect_b32 s49, s50, s49
	v_mbcnt_lo_u32_b32 v0, -1, 0
	v_mbcnt_hi_u32_b32 v0, -1, v0
	v_lshrrev_b32_e32 v22, 3, v0
	v_and_b32_e32 v23, 7, v0
	v_lshlrev_b32_e32 v2, 11, v22
	v_lshl_add_u32 v2, v23, 4, v2
	v_min_u32_e32 v50, 15, v0
	v_lshlrev_b32_e32 v50, 6, v50
	s_lshl_b32 s50, s47, 4
	v_lshl_add_u32 v24, v22, 1, s50
	v_lshlrev_b32_e32 v3, 8, v24
	v_lshl_add_u32 v3, v23, 5, v3
	v_lshlrev_b32_e32 v142, 5, v23
	v_lshlrev_b32_e32 v143, 2, v24
	v_add_u32_e32 v143, 0x5000, v143
	v_lshlrev_b32_e32 v144, 1, v24
	v_lshrrev_b32_e32 v25, 5, v0
	v_and_b32_e32 v26, 31, v0
	s_lshl_b32 s50, s47, 2
	v_add_u32_e32 v141, s50, v25
	v_lshlrev_b32_e32 v5, 2, v26
	v_lshlrev_b32_e32 v140, 8, v141
	v_lshl_add_u32 v140, v26, 3, v140
	v_lshlrev_b32_e32 v27, 3, v26
	s_lshl_b32 s50, s47, 3
	v_add_u32_e32 v145, s50, v22
	s_waitcnt lgkmcnt(0)
	s_lshl_b32 s50, s44, 12
	s_lshl_b32 s51, s46, 8
	s_add_u32 s50, s50, s51
	s_add_u32 s38, s38, s50
	s_addc_u32 s39, s39, 0
	s_add_u32 s40, s40, s50
	s_addc_u32 s41, s41, 0
	global_load_dwordx2 v[136:137], v27, s[38:39]
	global_load_dwordx2 v[138:139], v27, s[40:41]
	s_lshr_b32 s38, s45, 2
	s_mov_b32 s39, s47
	s_cmp_eq_u32 s38, 0
	s_cselect_b32 s40, 128, 64
	s_mul_i32 s41, s38, 70144
	s_mov_b32 s33, 0
	s_lshr_b32 s55, s43, 4
	s_and_b32 s56, s42, 1
	s_cmp_eq_u32 s38, 0
	s_cselect_b32 s50, s55, s56
	s_lshl_b32 s57, s42, 11
	s_add_u32 s57, s57, 0x2000
	s_lshl_b32 s58, s55, 2
	s_lshr_b32 s54, s42, 1
	s_add_u32 s58, s58, s54
	s_lshl_b32 s58, s58, 8
	s_movk_i32 s54, 0x7f0
	s_movk_i32 s56, 0xf0
	s_cmp_eq_u32 s38, 0
	s_cselect_b32 s0, s57, s58
	s_cselect_b32 s3, 31, 4
	s_cselect_b32 s52, 0xffff, 15
	s_cselect_b32 s54, s54, s56
	s_cmp_eq_u32 s50, 0
	s_cselect_b32 s54, 0, s54
	s_cselect_b32 s1, 16, -16
	s_add_u32 s0, s0, s54
	s_mul_i32 s48, s50, s49
	s_add_u32 s48, s48, s59
	s_lshl_b32 s54, s46, 7
	s_add_u32 s48, s48, s54
	s_cmp_lg_u32 s45, 0
	s_cbranch_scc1 .Lsc_noctr
	v_mov_b32_e32 v22, 0
	v_mov_b32_e32 v23, 0x24408
	ds_write_b32 v23, v22
	ds_write_b32 v23, v22 offset:4
.Lsc_noctr:
	s_lshr_b32 s54, s33, s3
	s_and_b32 s53, s33, s52
	s_lshl_b32 s54, s54, 11
	s_mul_i32 s55, s53, s1
	s_add_u32 s51, s0, s54
	s_add_u32 s51, s51, s55
	s_and_b32 s55, s33, 1
	s_mul_i32 s55, s55, 10496
	s_add_u32 s55, s55, s41
	s_lshl_b32 s57, s51, 11
	s_add_u32 s54, s48, s57
	s_add_u32 s30, s28, s54
	s_addc_u32 s31, s29, 0
	s_lshl_b32 s56, s39, 11
	s_add_u32 m0, s55, s56
	s_nop 0
	global_load_lds_dwordx4 v2, s[30:31]
	s_add_u32 s30, s30, 0x4000
	s_addc_u32 s31, s31, 0
	s_add_u32 m0, m0, 0x400
	s_nop 0
	global_load_lds_dwordx4 v2, s[30:31]
	s_cmp_gt_u32 s39, 1
	s_cbranch_scc1 .Lsc_isrn_1
	s_lshl_b32 s56, s39, 14
	s_add_u32 s54, s57, s56
	s_lshl_b32 s56, s46, 7
	s_add_u32 s54, s54, s56
	s_add_u32 s54, s54, 0x2bcda000
	s_add_u32 s30, s28, s54
	s_addc_u32 s31, s29, 0
	s_lshl_b32 s56, s39, 10
	s_add_u32 s56, s56, 8192
	s_add_u32 m0, s55, s56
	s_nop 0
	global_load_lds_dwordx4 v2, s[30:31]
	s_branch .Lsc_isd_2

.Lsc_isd_4:
	s_waitcnt vmcnt(0) lgkmcnt(0)
	s_barrier
	s_mov_b32 s33, 0
	s_lshr_b32 s54, s33, s3
	s_and_b32 s53, s33, s52
	s_lshl_b32 s54, s54, 11
	s_mul_i32 s55, s53, s1
	s_add_u32 s51, s0, s54
	s_add_u32 s51, s51, s55
	s_and_b32 s55, s33, 1
	s_mul_i32 s56, s55, 10496
	s_add_u32 s56, s56, s41
	s_mul_i32 s57, s55, 24576
	s_add_u32 s57, s57, s41
	s_add_u32 s57, s57, 20992
	s_sub_u32 s58, 0, s50
	s_and_b32 s58, s58, 15
	v_add_u32_e32 v22, 0, v141
	v_xor_b32_e32 v22, s58, v22
	v_lshl_add_u32 v23, v22, 7, v5
	v_lshlrev_b32_e32 v24, 2, v22
	v_add_u32_e32 v23, s56, v23
	v_add_u32_e32 v24, s56, v24
	ds_read2st64_b32 v[26:27], v23 offset0:0 offset1:8
	ds_read2st64_b32 v[30:31], v23 offset0:16 offset1:24
	ds_read_b32 v29, v23 offset:8192
	ds_read_b32 v28, v24 offset:10240
	v_add_u32_e32 v25, s57, v140
	s_waitcnt lgkmcnt(0)
	v_cvt_f32_f16_e32 v32, v27
	v_cvt_f32_f16_sdwa v33, v27 dst_sel:DWORD dst_unused:UNUSED_PAD src0_sel:WORD_1
	v_cvt_f32_f16_e32 v34, v31
	v_cvt_f32_f16_sdwa v35, v31 dst_sel:DWORD dst_unused:UNUSED_PAD src0_sel:WORD_1
	v_pk_mul_f32 v[36:37], v[136:137], v[28:29] op_sel_hi:[1,0]
	v_cvt_f32_f16_e32 v42, v26
	v_cvt_f32_f16_sdwa v43, v26 dst_sel:DWORD dst_unused:UNUSED_PAD src0_sel:WORD_1
	v_pk_mul_f32 v[36:37], v[36:37], v[32:33]
	v_pk_add_f32 v[40:41], v[34:35], -1.0 op_sel_hi:[1,0]
	v_cvt_f32_f16_e32 v44, v30
	v_pk_mul_f32 v[38:39], v[36:37], v[34:35]
	v_pk_fma_f32 v[40:41], v[40:41], v[138:139], 1.0 op_sel_hi:[1,1,0]
	v_cvt_f32_f16_sdwa v45, v30 dst_sel:DWORD dst_unused:UNUSED_PAD src0_sel:WORD_1
	ds_write2st64_b64 v25, v[36:37], v[38:39] offset0:0 offset1:8
	v_pk_mul_f32 v[40:41], v[40:41], v[32:33]
	v_cvt_f32_f16_e32 v26, v29
	v_cvt_f32_f16_sdwa v27, v29 dst_sel:DWORD dst_unused:UNUSED_PAD src0_sel:WORD_1
	ds_write2st64_b64 v25, v[40:41], v[42:43] offset0:16 offset1:24
	s_nop 0
	ds_write2st64_b64 v25, v[44:45], v[26:27] offset0:32 offset1:40
	v_add_u32_e32 v22, 2, v141
	v_xor_b32_e32 v22, s58, v22
	v_lshl_add_u32 v23, v22, 7, v5
	v_lshlrev_b32_e32 v24, 2, v22
	v_add_u32_e32 v23, s56, v23
	v_add_u32_e32 v24, s56, v24
	ds_read2st64_b32 v[26:27], v23 offset0:0 offset1:8
	ds_read2st64_b32 v[30:31], v23 offset0:16 offset1:24
	ds_read_b32 v29, v23 offset:8192
	ds_read_b32 v28, v24 offset:10240
	v_add_u32_e32 v25, s57, v140
	s_waitcnt lgkmcnt(0)
	v_cvt_f32_f16_e32 v32, v27
	v_cvt_f32_f16_sdwa v33, v27 dst_sel:DWORD dst_unused:UNUSED_PAD src0_sel:WORD_1
	v_cvt_f32_f16_e32 v34, v31
	v_cvt_f32_f16_sdwa v35, v31 dst_sel:DWORD dst_unused:UNUSED_PAD src0_sel:WORD_1
	v_pk_mul_f32 v[36:37], v[136:137], v[28:29] op_sel_hi:[1,0]
	v_cvt_f32_f16_e32 v42, v26
	v_cvt_f32_f16_sdwa v43, v26 dst_sel:DWORD dst_unused:UNUSED_PAD src0_sel:WORD_1
	v_pk_mul_f32 v[36:37], v[36:37], v[32:33]
	v_pk_add_f32 v[40:41], v[34:35], -1.0 op_sel_hi:[1,0]
	v_cvt_f32_f16_e32 v44, v30
	v_pk_mul_f32 v[38:39], v[36:37], v[34:35]
	v_pk_fma_f32 v[40:41], v[40:41], v[138:139], 1.0 op_sel_hi:[1,1,0]
	v_cvt_f32_f16_sdwa v45, v30 dst_sel:DWORD dst_unused:UNUSED_PAD src0_sel:WORD_1
	ds_write2st64_b64 v25, v[36:37], v[38:39] offset0:1 offset1:9
	v_pk_mul_f32 v[40:41], v[40:41], v[32:33]
	v_cvt_f32_f16_e32 v26, v29
	v_cvt_f32_f16_sdwa v27, v29 dst_sel:DWORD dst_unused:UNUSED_PAD src0_sel:WORD_1
	ds_write2st64_b64 v25, v[40:41], v[42:43] offset0:17 offset1:25
	s_nop 0
	ds_write2st64_b64 v25, v[44:45], v[26:27] offset0:33 offset1:41
	s_waitcnt lgkmcnt(0)
	s_barrier
	s_mov_b32 s33, 0
.Lsc_loop:
	s_and_b32 s55, s33, 1
	s_mul_i32 s56, s55, 24576
	s_add_u32 s56, s56, s41
	s_add_u32 s56, s56, 20992
	v_add_u32_e32 v47, s56, v142
	v_add_u32_e32 v48, s56, v143
	s_lshl_b32 s55, s55, 11
	s_lshl_b32 s56, s38, 12
	s_add_u32 s55, s55, s56
	s_add_u32 s55, s55, 140288
	v_add_u32_e32 v49, s55, v144
	ds_read_b128 v[52:55], v47 offset:0
	ds_read_b128 v[56:59], v47 offset:16
	ds_read_b128 v[68:71], v47 offset:8192
	ds_read_b128 v[72:75], v47 offset:8208
	ds_read_b64 v[92:93], v48 offset:0
	ds_read_b128 v[84:87], v47 offset:16384
	ds_read_b128 v[88:91], v47 offset:16400
	ds_read_b128 v[60:63], v47 offset:4096
	ds_read_b128 v[64:67], v47 offset:4112
	ds_read_b128 v[76:79], v47 offset:12288
	ds_read_b128 v[80:83], v47 offset:12304
	s_cmp_gt_u32 s39, 1
	s_cbranch_scc1 .Lsc_issue
	s_cmp_eq_u32 s33, 0
	s_cbranch_scc1 .Lsc_issue
	s_sub_u32 s47, s33, 1
	s_lshr_b32 s54, s47, s3
	s_and_b32 s53, s47, s52
	s_lshl_b32 s54, s54, 11
	s_mul_i32 s55, s53, s1
	s_add_u32 s51, s0, s54
	s_add_u32 s51, s51, s55
	s_and_b32 s55, s47, 1
	s_lshl_b32 s55, s55, 11
	s_lshl_b32 s56, s38, 12
	s_add_u32 s55, s55, s56
	s_add_u32 s55, s55, 140288
	v_and_b32_e32 v23, 7, v0
	v_lshlrev_b32_e32 v23, 4, v23
	v_lshl_add_u32 v22, v145, 7, v23
	v_add_u32_e32 v22, s55, v22
	ds_read_b128 v[24:27], v22
	s_sub_u32 s58, 0, s50
	s_and_b32 s58, s58, 15
	v_xor_b32_e32 v22, s58, v145
	v_lshl_add_u32 v22, v22, 11, v23
	s_mul_i32 s54, s50, 0x3000000
	s_add_u32 s54, s54, 0xa0da000
	s_lshl_b32 s56, s51, 11
	s_add_u32 s54, s54, s56
	s_lshl_b32 s56, s46, 7
	s_add_u32 s54, s54, s56
	s_add_u32 s30, s28, s54
	s_addc_u32 s31, s29, 0
	s_waitcnt lgkmcnt(0)
	global_store_dwordx4 v22, v[24:27], s[30:31]

.Lsc_isd_6:
.Lsc_prep:
	s_add_u32 s47, s33, 1
	s_cmp_lt_u32 s47, s40
	s_cbranch_scc0 .Lsc_noprep
	s_lshr_b32 s54, s47, s3
	s_and_b32 s53, s47, s52
	s_lshl_b32 s54, s54, 11
	s_mul_i32 s55, s53, s1
	s_add_u32 s51, s0, s54
	s_add_u32 s51, s51, s55
	s_and_b32 s55, s47, 1
	s_mul_i32 s56, s55, 10496
	s_add_u32 s56, s56, s41
	s_mul_i32 s57, s55, 24576
	s_add_u32 s57, s57, s41
	s_add_u32 s57, s57, 20992
	s_sub_u32 s58, 0, s50
	s_and_b32 s58, s58, 15
	v_add_u32_e32 v22, 0, v141
	v_xor_b32_e32 v22, s58, v22
	v_lshl_add_u32 v23, v22, 7, v5
	v_lshlrev_b32_e32 v24, 2, v22
	v_add_u32_e32 v23, s56, v23
	v_add_u32_e32 v24, s56, v24
	ds_read2st64_b32 v[26:27], v23 offset0:0 offset1:8
	ds_read2st64_b32 v[30:31], v23 offset0:16 offset1:24
	ds_read_b32 v29, v23 offset:8192
	ds_read_b32 v28, v24 offset:10240
	v_add_u32_e32 v25, s57, v140
	s_waitcnt lgkmcnt(0)
	v_cvt_f32_f16_e32 v32, v27
	v_cvt_f32_f16_sdwa v33, v27 dst_sel:DWORD dst_unused:UNUSED_PAD src0_sel:WORD_1
	v_cvt_f32_f16_e32 v34, v31
	v_cvt_f32_f16_sdwa v35, v31 dst_sel:DWORD dst_unused:UNUSED_PAD src0_sel:WORD_1
	v_pk_mul_f32 v[36:37], v[136:137], v[28:29] op_sel_hi:[1,0]
	v_cvt_f32_f16_e32 v42, v26
	v_cvt_f32_f16_sdwa v43, v26 dst_sel:DWORD dst_unused:UNUSED_PAD src0_sel:WORD_1
	v_pk_mul_f32 v[36:37], v[36:37], v[32:33]
	v_pk_add_f32 v[40:41], v[34:35], -1.0 op_sel_hi:[1,0]
	v_cvt_f32_f16_e32 v44, v30
	v_pk_mul_f32 v[38:39], v[36:37], v[34:35]
	v_pk_fma_f32 v[40:41], v[40:41], v[138:139], 1.0 op_sel_hi:[1,1,0]
	v_cvt_f32_f16_sdwa v45, v30 dst_sel:DWORD dst_unused:UNUSED_PAD src0_sel:WORD_1
	ds_write2st64_b64 v25, v[36:37], v[38:39] offset0:0 offset1:8
	v_pk_mul_f32 v[40:41], v[40:41], v[32:33]
	v_cvt_f32_f16_e32 v26, v29
	v_cvt_f32_f16_sdwa v27, v29 dst_sel:DWORD dst_unused:UNUSED_PAD src0_sel:WORD_1
	ds_write2st64_b64 v25, v[40:41], v[42:43] offset0:16 offset1:24
	s_nop 0
	ds_write2st64_b64 v25, v[44:45], v[26:27] offset0:32 offset1:40
	v_add_u32_e32 v22, 2, v141
	v_xor_b32_e32 v22, s58, v22
	v_lshl_add_u32 v23, v22, 7, v5
	v_lshlrev_b32_e32 v24, 2, v22
	v_add_u32_e32 v23, s56, v23
	v_add_u32_e32 v24, s56, v24
	ds_read2st64_b32 v[26:27], v23 offset0:0 offset1:8
	ds_read2st64_b32 v[30:31], v23 offset0:16 offset1:24
	ds_read_b32 v29, v23 offset:8192
	ds_read_b32 v28, v24 offset:10240
	v_add_u32_e32 v25, s57, v140
	s_waitcnt lgkmcnt(0)
	v_cvt_f32_f16_e32 v32, v27
	v_cvt_f32_f16_sdwa v33, v27 dst_sel:DWORD dst_unused:UNUSED_PAD src0_sel:WORD_1
	v_cvt_f32_f16_e32 v34, v31
	v_cvt_f32_f16_sdwa v35, v31 dst_sel:DWORD dst_unused:UNUSED_PAD src0_sel:WORD_1
	v_pk_mul_f32 v[36:37], v[136:137], v[28:29] op_sel_hi:[1,0]
	v_cvt_f32_f16_e32 v42, v26
	v_cvt_f32_f16_sdwa v43, v26 dst_sel:DWORD dst_unused:UNUSED_PAD src0_sel:WORD_1
	v_pk_mul_f32 v[36:37], v[36:37], v[32:33]
	v_pk_add_f32 v[40:41], v[34:35], -1.0 op_sel_hi:[1,0]
	v_cvt_f32_f16_e32 v44, v30
	v_pk_mul_f32 v[38:39], v[36:37], v[34:35]
	v_pk_fma_f32 v[40:41], v[40:41], v[138:139], 1.0 op_sel_hi:[1,1,0]
	v_cvt_f32_f16_sdwa v45, v30 dst_sel:DWORD dst_unused:UNUSED_PAD src0_sel:WORD_1
	ds_write2st64_b64 v25, v[36:37], v[38:39] offset0:1 offset1:9
	v_pk_mul_f32 v[40:41], v[40:41], v[32:33]
	v_cvt_f32_f16_e32 v26, v29
	v_cvt_f32_f16_sdwa v27, v29 dst_sel:DWORD dst_unused:UNUSED_PAD src0_sel:WORD_1
	ds_write2st64_b64 v25, v[40:41], v[42:43] offset0:17 offset1:25
	s_nop 0
	ds_write2st64_b64 v25, v[44:45], v[26:27] offset0:33 offset1:41
.Lsc_noprep:
	s_lshr_b32 s54, s33, s3
	s_and_b32 s53, s33, s52
	s_lshl_b32 s54, s54, 11
	s_mul_i32 s55, s53, s1
	s_add_u32 s51, s0, s54
	s_add_u32 s51, s51, s55
	s_cmp_lg_u32 s53, 0
	s_cbranch_scc1 .Lsc_noinit
	s_cmp_eq_u32 s38, 0
	s_cbranch_scc0 .Lsc_zinit
	s_lshr_b32 s55, s33, 4
	s_lshl_b32 s55, s55, 1
	s_lshr_b32 s56, s43, 4
	s_add_u32 s55, s55, s56
	s_lshl_b32 s55, s55, 2
	s_lshr_b32 s56, s42, 1
	s_add_u32 s55, s55, s56
	s_cmp_eq_u32 s38, 0
	s_cselect_b32 s54, s42, s55
	s_lshl_b32 s54, s54, 1
	s_add_u32 s54, s54, s44
	s_lshl_b32 s54, s54, 1
	s_add_u32 s54, s54, s50
	s_lshl_b32 s54, s54, 4
	s_add_u32 s54, s54, s46
	s_lshl_b32 s54, s54, 14
	s_add_u32 s30, s36, s54
	s_addc_u32 s31, s37, 0
	global_load_dwordx4 v[6:9], v3, s[30:31]
	global_load_dwordx4 v[10:13], v3, s[30:31] offset:16
	global_load_dwordx4 v[14:17], v3, s[30:31] offset:256
	global_load_dwordx4 v[18:21], v3, s[30:31] offset:272
	s_waitcnt vmcnt(0)
	s_branch .Lsc_noinit

.Lsc_nofin:
	s_waitcnt vmcnt(0) lgkmcnt(0)
	s_lshl_b32 s54, s38, 2
	s_add_u32 s54, s54, 0x24408
	v_mov_b32_e32 v22, s54
	v_mov_b32_e32 v23, 1
	s_mov_b64 exec, 1
	ds_add_u32 v22, v23
	s_mov_b64 exec, -1
	s_add_u32 s55, s33, 1
	s_lshl_b32 s55, s55, 2
	s_mov_b32 s56, 0
.Lsc_spin:
	ds_read_b32 v24, v22
	s_waitcnt lgkmcnt(0)
	v_readfirstlane_b32 s57, v24
	s_cmp_ge_u32 s57, s55
	s_cbranch_scc1 .Lsc_spun
	s_sleep 1
	s_add_u32 s56, s56, 1
	s_cmp_lt_u32 s56, 0x40000
	s_cbranch_scc1 .Lsc_spin
.Lsc_spun:
	s_add_u32 s33, s33, 1
	s_cmp_lt_u32 s33, s40
	s_cbranch_scc1 .Lsc_loop
	s_cmp_gt_u32 s39, 1
	s_cbranch_scc1 .Lsc_done
	s_sub_u32 s47, s40, 1
	s_lshr_b32 s54, s47, s3
	s_and_b32 s53, s47, s52
	s_lshl_b32 s54, s54, 11
	s_mul_i32 s55, s53, s1
	s_add_u32 s51, s0, s54
	s_add_u32 s51, s51, s55
	s_and_b32 s55, s47, 1
	s_lshl_b32 s55, s55, 11
	s_lshl_b32 s56, s38, 12
	s_add_u32 s55, s55, s56
	s_add_u32 s55, s55, 140288
	v_and_b32_e32 v23, 7, v0
	v_lshlrev_b32_e32 v23, 4, v23
	v_lshl_add_u32 v22, v145, 7, v23
	v_add_u32_e32 v22, s55, v22
	ds_read_b128 v[24:27], v22
	s_sub_u32 s58, 0, s50
	s_and_b32 s58, s58, 15
	v_xor_b32_e32 v22, s58, v145
	v_lshl_add_u32 v22, v22, 11, v23
	s_mul_i32 s54, s50, 0x3000000
	s_add_u32 s54, s54, 0xa0da000
	s_lshl_b32 s56, s51, 11
	s_add_u32 s54, s54, s56
	s_lshl_b32 s56, s46, 7
	s_add_u32 s54, s54, s56
	s_add_u32 s30, s28, s54
	s_addc_u32 s31, s29, 0
	s_waitcnt lgkmcnt(0)
	global_store_dwordx4 v22, v[24:27], s[30:31]
.Lsc_done:
	v_readlane_b32 s47, v253, 37
	s_movk_i32 s59, 0x1a00
